# plus l1rows phase: row-0 rope-key loads no longer drained before row-1 loads are issued (both rows in flight)
# speedup vs baseline: 1.0012x; 1.0012x over previous
; DEVI float bf2f(unsigned short h) { return __uint_as_float(((unsigned)h) << 16); }
; DEVI void phase_l1rows(const Params& p) {
;     ...
;         for (int rr = 0; rr < 2; ++rr) {
;             const bf16_t* r = IN1 + (size_t)(rowb + rr) * 1792;
;             unpack8(*(const u32x4*)(r + 512 + lane * 8), v[rr]);
;             u32x4 z = {0u, 0u, 0u, 0u};
;             unpack8(lane < 48 ? *(const u32x4*)(r + 1024 + lane * 8) : z, cq[rr]);
;             unpack8(lane < 32 ? *(const u32x4*)(r + 1408 + lane * 8) : z, kv[rr]);
;             x1[rr] = lane < 16 ? bf2f(r[1664 + lane]) : 0.f; x2[rr] = lane < 16 ? bf2f(r[1680 + lane]) : 0.f;
;         }
.LBB0_409:
	s_or_b64 exec, exec, s[0:1]
	s_and_saveexec_b64 s[0:1], s[42:43]
	s_xor_b64 s[0:1], exec, s[0:1]
	v_mov_b32_e32 v84, v1
	s_or_saveexec_b64 s[0:1], s[0:1]
	v_mov_b32_e32 v14, 0
	v_lshlrev_b32_e32 v70, 1, v26
	v_mov_b32_e32 v118, 0
	s_xor_b64 exec, exec, s[0:1]
	s_cbranch_execz .LBB0_413
	v_mov_b32_e32 v71, v1
	v_lshl_add_u64 v[16:17], v[78:79], 0, v[70:71]
	global_load_ushort v150, v[16:17], off offset:3328
	s_nop 0
	global_load_ushort v151, v[16:17], off offset:3360

; DEVI float bf2f(unsigned short h) { return __uint_as_float(((unsigned)h) << 16); }
; DEVI void phase_l1rows(const Params& p) {
;     ...
;             unpack8(*(const u32x4*)(r + 512 + lane * 8), v[rr]);
;             u32x4 z = {0u, 0u, 0u, 0u};
;             unpack8(lane < 48 ? *(const u32x4*)(r + 1024 + lane * 8) : z, cq[rr]);
;             unpack8(lane < 32 ? *(const u32x4*)(r + 1408 + lane * 8) : z, kv[rr]);
;             x1[rr] = lane < 16 ? bf2f(r[1664 + lane]) : 0.f; x2[rr] = lane < 16 ? bf2f(r[1680 + lane]) : 0.f;
;         }
;         float sv[2], sq[2], sk[2];
; #pragma unroll
;         for (int rr = 0; rr < 2; ++rr) {
;             sv[rr] = 0.f; sq[rr] = 0.f; sk[rr] = 0.f;
; #pragma unroll
;             for (int k = 0; k < 8; ++k) { sv[rr] += v[rr][k]; sq[rr] += cq[rr][k] * cq[rr][k]; sk[rr] += kv[rr][k] * kv[rr][k]; }
;         }
; #pragma unroll
;         for (int of = 32; of > 0; of >>= 1)
; #pragma unroll
;             for (int rr = 0; rr < 2; ++rr) { sv[rr] += __shfl_xor(sv[rr], of); sq[rr] += __shfl_xor(sq[rr], of); sk[rr] += __shfl_xor(sk[rr], of); }
.LBB0_421:
	s_or_b64 exec, exec, s[0:1]
	s_waitcnt vmcnt(0)
	s_mov_b64 s[0:1], exec
	s_andn2_b64 exec, exec, s[42:43]
	v_lshlrev_b32_e32 v84, 16, v150
	v_lshlrev_b32_e32 v118, 16, v151
	s_mov_b64 exec, s[0:1]
	v_lshlrev_b32_e32 v100, 16, v18
	v_and_b32_e32 v101, 0xffff0000, v18
	v_lshlrev_b32_e32 v102, 16, v19
	v_and_b32_e32 v103, 0xffff0000, v19
	v_lshlrev_b32_e32 v18, 16, v10
	v_and_b32_e32 v19, 0xffff0000, v10
	v_lshlrev_b32_e32 v94, 16, v6
	v_and_b32_e32 v95, 0xffff0000, v6
	v_lshlrev_b32_e32 v6, 16, v2
	v_lshlrev_b32_e32 v108, 16, v20
	v_and_b32_e32 v109, 0xffff0000, v20
	v_lshlrev_b32_e32 v110, 16, v21
	v_and_b32_e32 v111, 0xffff0000, v21
	v_lshlrev_b32_e32 v20, 16, v11
	v_and_b32_e32 v21, 0xffff0000, v11
	v_lshlrev_b32_e32 v98, 16, v7
	v_and_b32_e32 v99, 0xffff0000, v7
	v_and_b32_e32 v7, 0xffff0000, v2
	v_add_f32_e32 v33, 0, v6
	v_pk_mul_f32 v[104:105], v[94:95], v[94:95]
	v_pk_mul_f32 v[106:107], v[18:19], v[18:19]
	v_lshlrev_b32_e32 v2, 16, v3
	v_add_f32_e32 v33, v33, v7
	v_pk_mul_f32 v[122:123], v[20:21], v[20:21]
	v_add_f32_e32 v71, v104, v105
	v_add_f32_e32 v104, v106, v107
	v_lshlrev_b32_e32 v10, 16, v12
	v_and_b32_e32 v11, 0xffff0000, v12
	v_and_b32_e32 v3, 0xffff0000, v3
	v_add_f32_e32 v33, v33, v2
	v_add_f32_e32 v104, v122, v104
	v_lshlrev_b32_e32 v92, 16, v8
	v_and_b32_e32 v93, 0xffff0000, v8
	v_lshlrev_b32_e32 v8, 16, v4
	v_add_f32_e32 v33, v33, v3
	v_pk_mul_f32 v[126:127], v[10:11], v[10:11]
	v_add_f32_e32 v104, v123, v104
	v_lshlrev_b32_e32 v12, 16, v13
	v_and_b32_e32 v13, 0xffff0000, v13
	v_lshlrev_b32_e32 v96, 16, v9
	v_and_b32_e32 v97, 0xffff0000, v9
	v_and_b32_e32 v9, 0xffff0000, v4
	v_add_f32_e32 v33, v33, v8
	v_add_f32_e32 v104, v126, v104
	v_lshlrev_b32_e32 v4, 16, v5
	v_add_f32_e32 v33, v33, v9
	v_pk_mul_f32 v[130:131], v[12:13], v[12:13]
	v_add_f32_e32 v104, v127, v104
	v_lshlrev_b32_e32 v80, 16, v22
	v_and_b32_e32 v81, 0xffff0000, v22
	v_lshlrev_b32_e32 v88, 16, v14
	v_and_b32_e32 v89, 0xffff0000, v14
	v_and_b32_e32 v5, 0xffff0000, v5
	v_pk_mul_f32 v[120:121], v[98:99], v[98:99]
	v_add_f32_e32 v33, v33, v4
	v_add_f32_e32 v104, v130, v104
	v_add_f32_e32 v33, v33, v5
	v_add_f32_e32 v71, v120, v71
	v_add_f32_e32 v119, v131, v104
	v_pk_mul_f32 v[104:105], v[88:89], v[88:89]
	v_pk_mul_f32 v[106:107], v[80:81], v[80:81]
	v_pk_mul_f32 v[124:125], v[92:93], v[92:93]
	v_add_f32_e32 v71, v121, v71
	v_add_f32_e32 v104, v104, v105
	v_add_f32_e32 v105, v106, v107
	ds_bpermute_b32 v106, v112, v33
	v_add_f32_e32 v71, v124, v71
	v_pk_mul_f32 v[128:129], v[96:97], v[96:97]
	v_add_f32_e32 v71, v125, v71
	v_add_f32_e32 v71, v128, v71
	v_add_f32_e32 v71, v129, v71
	s_waitcnt lgkmcnt(0)
	v_add_f32_e32 v33, v33, v106
	ds_bpermute_b32 v106, v112, v71
	v_add_f32_e32 v120, 0, v100
	v_lshlrev_b32_e32 v90, 16, v15
	v_and_b32_e32 v91, 0xffff0000, v15
	v_add_f32_e32 v120, v120, v101
	v_add_f32_e32 v124, v120, v102
	v_pk_mul_f32 v[120:121], v[90:91], v[90:91]
	v_lshlrev_b32_e32 v14, 16, v16
	v_and_b32_e32 v15, 0xffff0000, v16
	v_add_f32_e32 v124, v124, v103
	v_add_f32_e32 v104, v120, v104
	v_add_f32_e32 v128, v124, v108
	v_pk_mul_f32 v[124:125], v[14:15], v[14:15]
	v_add_f32_e32 v104, v121, v104
	s_waitcnt lgkmcnt(0)
	v_add_f32_e32 v71, v71, v106
	ds_bpermute_b32 v106, v112, v119
	v_lshlrev_b32_e32 v16, 16, v17
	v_and_b32_e32 v17, 0xffff0000, v17
	v_add_f32_e32 v128, v128, v109
	v_add_f32_e32 v104, v124, v104
	v_lshlrev_b32_e32 v82, 16, v23
	v_and_b32_e32 v83, 0xffff0000, v23
	v_add_f32_e32 v132, v128, v110
	v_pk_mul_f32 v[128:129], v[16:17], v[16:17]
	v_add_f32_e32 v104, v125, v104
	v_pk_mul_f32 v[122:123], v[82:83], v[82:83]
	v_add_f32_e32 v104, v128, v104
	v_lshlrev_b32_e32 v22, 16, v24
	v_and_b32_e32 v23, 0xffff0000, v24
	v_add_f32_e32 v104, v129, v104
	v_add_f32_e32 v105, v122, v105
	v_pk_mul_f32 v[126:127], v[22:23], v[22:23]
	v_add_f32_e32 v105, v123, v105
	s_waitcnt lgkmcnt(0)
	v_add_f32_e32 v106, v119, v106
	ds_bpermute_b32 v119, v112, v104
	v_lshlrev_b32_e32 v24, 16, v25
	v_and_b32_e32 v25, 0xffff0000, v25
	v_add_f32_e32 v105, v126, v105
	v_pk_mul_f32 v[130:131], v[24:25], v[24:25]
	v_add_f32_e32 v105, v127, v105
	v_add_f32_e32 v105, v130, v105
	v_add_f32_e32 v105, v131, v105
	s_waitcnt lgkmcnt(0)
	v_add_f32_e32 v104, v104, v119
	ds_bpermute_b32 v119, v112, v105
	v_add_f32_e32 v132, v132, v111
	ds_bpermute_b32 v107, v112, v132
	s_waitcnt lgkmcnt(1)
	v_add_f32_e32 v105, v105, v119
	s_waitcnt lgkmcnt(0)
	v_add_f32_e32 v107, v132, v107
	ds_bpermute_b32 v144, v113, v33
	ds_bpermute_b32 v145, v113, v71
	ds_bpermute_b32 v146, v113, v106
	ds_bpermute_b32 v147, v113, v107
	ds_bpermute_b32 v148, v113, v104
	ds_bpermute_b32 v149, v113, v105
	s_waitcnt lgkmcnt(5)
	v_add_f32_e32 v33, v33, v144
	s_waitcnt lgkmcnt(4)
	v_add_f32_e32 v71, v71, v145
	s_waitcnt lgkmcnt(3)
	v_add_f32_e32 v106, v106, v146
	s_waitcnt lgkmcnt(2)
	v_add_f32_e32 v107, v107, v147
	s_waitcnt lgkmcnt(1)
	v_add_f32_e32 v104, v104, v148
	s_waitcnt lgkmcnt(0)
	v_add_f32_e32 v105, v105, v149
	ds_bpermute_b32 v144, v114, v33
	ds_bpermute_b32 v145, v114, v71
	ds_bpermute_b32 v146, v114, v106
	ds_bpermute_b32 v147, v114, v107
	ds_bpermute_b32 v148, v114, v104
	ds_bpermute_b32 v149, v114, v105
	s_waitcnt lgkmcnt(5)
	v_add_f32_e32 v33, v33, v144
	s_waitcnt lgkmcnt(4)
	v_add_f32_e32 v71, v71, v145
	s_waitcnt lgkmcnt(3)
; DEVI u32x4 pack8(const float* f) { u32x4 w; w.x = pk2(f[0], f[1]); w.y = pk2(f[2], f[3]); w.z = pk2(f[4], f[5]); w.w = pk2(f[6], f[7]); return w; }
; DEVI void phase_l1rows(const Params& p) {
;     ...
; #pragma unroll
;         for (int of = 32; of > 0; of >>= 1)
; #pragma unroll
;             for (int rr = 0; rr < 2; ++rr) { sv[rr] += __shfl_xor(sv[rr], of); sq[rr] += __shfl_xor(sq[rr], of); sk[rr] += __shfl_xor(sk[rr], of); }
;         float var[2];
; #pragma unroll
;         for (int rr = 0; rr < 2; ++rr) {
;             const float mu = sv[rr] * (1.f / 512.f); var[rr] = 0.f;
; #pragma unroll
;             for (int k = 0; k < 8; ++k) { v[rr][k] -= mu; var[rr] += v[rr][k] * v[rr][k]; }
;         }
; #pragma unroll
;         for (int of = 32; of > 0; of >>= 1) { var[0] += __shfl_xor(var[0], of); var[1] += __shfl_xor(var[1], of); }
; #pragma unroll
;         for (int rr = 0; rr < 2; ++rr) {
;             const int row = rowb + rr;
;             bf16_t* r = IN1 + (size_t)row * 1792;
;             {
;                 const float rs = rsqrtf(var[rr] * (1.f / 512.f) + EPS);
; #pragma unroll
;                 for (int k = 0; k < 8; ++k) v[rr][k] = v[rr][k] * rs * glng[k] + glnb[k];
;                 *(u32x4*)(r + 512 + lane * 8) = pack8(v[rr]);
;                 if (row >= NP) {
;                     float* o = p.out + O_SGUV_S + (size_t)(row - NP) * 512 + lane * 8;
;                     *(f32x4*)o = (f32x4){v[rr][0], v[rr][1], v[rr][2], v[rr][3]}; *(f32x4*)(o + 4) = (f32x4){v[rr][4], v[rr][5], v[rr][6], v[rr][7]};
;                 }
	v_add_f32_e32 v106, v106, v146
	s_waitcnt lgkmcnt(2)
	v_add_f32_e32 v107, v107, v147
	s_waitcnt lgkmcnt(1)
	v_add_f32_e32 v104, v104, v148
	s_waitcnt lgkmcnt(0)
	v_add_f32_e32 v105, v105, v149
	ds_bpermute_b32 v144, v115, v33
	ds_bpermute_b32 v145, v115, v71
	ds_bpermute_b32 v146, v115, v106
	ds_bpermute_b32 v147, v115, v107
	ds_bpermute_b32 v148, v115, v104
	ds_bpermute_b32 v149, v115, v105
	s_waitcnt lgkmcnt(5)
	v_add_f32_e32 v33, v33, v144
	s_waitcnt lgkmcnt(4)
	v_add_f32_e32 v71, v71, v145
	s_waitcnt lgkmcnt(3)
	v_add_f32_e32 v106, v106, v146
	s_waitcnt lgkmcnt(2)
	v_add_f32_e32 v107, v107, v147
	s_waitcnt lgkmcnt(1)
	v_add_f32_e32 v104, v104, v148
	s_waitcnt lgkmcnt(0)
	v_add_f32_e32 v105, v105, v149
	ds_bpermute_b32 v119, v116, v33
	s_waitcnt lgkmcnt(0)
	v_add_f32_e32 v121, v33, v119
	ds_bpermute_b32 v33, v116, v71
	s_waitcnt lgkmcnt(0)
	v_add_f32_e32 v71, v71, v33
	ds_bpermute_b32 v33, v116, v106
	ds_bpermute_b32 v124, v117, v71
	s_waitcnt lgkmcnt(1)
	v_add_f32_e32 v33, v106, v33
	ds_bpermute_b32 v106, v116, v107
	ds_bpermute_b32 v123, v117, v33
	s_waitcnt lgkmcnt(1)
	v_add_f32_e32 v106, v107, v106
	ds_bpermute_b32 v107, v116, v104
	s_waitcnt lgkmcnt(0)
	v_add_f32_e32 v120, v104, v107
	ds_bpermute_b32 v104, v116, v105
	ds_bpermute_b32 v122, v117, v120
	s_waitcnt lgkmcnt(1)
	v_add_f32_e32 v119, v105, v104
	ds_bpermute_b32 v105, v117, v106
	ds_bpermute_b32 v104, v117, v121
	s_waitcnt lgkmcnt(1)
	v_add_f32_e32 v105, v106, v105
	s_waitcnt lgkmcnt(0)
	v_add_f32_e32 v104, v121, v104
	v_mul_f32_e32 v128, 0x3b000000, v105
	v_mul_f32_e32 v126, 0x3b000000, v104
	v_pk_add_f32 v[104:105], v[100:101], v[128:129] op_sel_hi:[1,0] neg_lo:[0,1] neg_hi:[0,1]
	v_pk_add_f32 v[106:107], v[102:103], v[128:129] op_sel_hi:[1,0] neg_lo:[0,1] neg_hi:[0,1]
	v_pk_mul_f32 v[130:131], v[104:105], v[104:105]
	v_pk_mul_f32 v[132:133], v[106:107], v[106:107]
	v_add_f32_e32 v125, v130, v131
	v_pk_add_f32 v[100:101], v[108:109], v[128:129] op_sel_hi:[1,0] neg_lo:[0,1] neg_hi:[0,1]
	v_add_f32_e32 v125, v132, v125
	v_pk_mul_f32 v[108:109], v[100:101], v[100:101]
	v_add_f32_e32 v125, v133, v125
	v_pk_add_f32 v[102:103], v[110:111], v[128:129] op_sel_hi:[1,0] neg_lo:[0,1] neg_hi:[0,1]
	v_add_f32_e32 v108, v108, v125
	v_pk_mul_f32 v[110:111], v[102:103], v[102:103]
	v_add_f32_e32 v108, v109, v108
	v_add_f32_e32 v108, v110, v108
	v_add_f32_e32 v108, v111, v108
	ds_bpermute_b32 v109, v112, v108
	v_pk_add_f32 v[6:7], v[6:7], v[126:127] op_sel_hi:[1,0] neg_lo:[0,1] neg_hi:[0,1]
	v_pk_add_f32 v[2:3], v[2:3], v[126:127] op_sel_hi:[1,0] neg_lo:[0,1] neg_hi:[0,1]
	v_pk_mul_f32 v[128:129], v[6:7], v[6:7]
	v_pk_mul_f32 v[130:131], v[2:3], v[2:3]
	s_waitcnt lgkmcnt(0)
	v_add_f32_e32 v108, v108, v109
	ds_bpermute_b32 v109, v113, v108
	v_pk_add_f32 v[132:133], v[8:9], v[126:127] op_sel_hi:[1,0] neg_lo:[0,1] neg_hi:[0,1]
	v_pk_add_f32 v[4:5], v[4:5], v[126:127] op_sel_hi:[1,0] neg_lo:[0,1] neg_hi:[0,1]
	v_pk_mul_f32 v[8:9], v[132:133], v[132:133]
	v_pk_mul_f32 v[126:127], v[4:5], v[4:5]
	s_waitcnt lgkmcnt(0)
	v_add_f32_e32 v108, v108, v109
	ds_bpermute_b32 v109, v114, v108
	ds_bpermute_b32 v121, v117, v119
	s_waitcnt lgkmcnt(1)
	v_add_f32_e32 v108, v108, v109
	ds_bpermute_b32 v109, v115, v108
	s_waitcnt lgkmcnt(0)
	v_add_f32_e32 v108, v108, v109
	ds_bpermute_b32 v109, v116, v108
	s_waitcnt lgkmcnt(0)
	v_add_f32_e32 v110, v108, v109
	v_add_f32_e32 v109, v128, v129
	v_add_f32_e32 v109, v130, v109
	v_add_f32_e32 v109, v131, v109
	v_add_f32_e32 v8, v8, v109
	v_add_f32_e32 v8, v9, v8
	v_add_f32_e32 v8, v126, v8
	v_add_f32_e32 v8, v127, v8
	ds_bpermute_b32 v9, v112, v8
	ds_bpermute_b32 v111, v117, v110
	v_add_u32_e32 v108, 0xffff0000, v62
	s_waitcnt lgkmcnt(1)
	v_add_f32_e32 v8, v8, v9
	ds_bpermute_b32 v9, v113, v8
	s_waitcnt lgkmcnt(0)
	v_add_f32_e32 v8, v8, v9
	ds_bpermute_b32 v9, v114, v8
	s_waitcnt lgkmcnt(0)
	v_add_f32_e32 v8, v8, v9
	ds_bpermute_b32 v9, v115, v8
	s_waitcnt lgkmcnt(0)
	v_add_f32_e32 v8, v8, v9
	ds_bpermute_b32 v9, v116, v8
	s_waitcnt lgkmcnt(0)
	v_add_f32_e32 v8, v8, v9
	ds_bpermute_b32 v9, v117, v8
	s_waitcnt lgkmcnt(0)
	v_add_f32_e32 v8, v8, v9
	v_fmamk_f32 v8, v8, 0x3b000000, v246
	v_cmp_gt_f32_e64 s[0:1], s34, v8
	v_mul_f32_e32 v9, 0x4b800000, v8
	s_nop 0
	v_cndmask_b32_e64 v8, v8, v9, s[0:1]
	v_rsq_f32_e32 v8, v8
	s_nop 0
	v_mul_f32_e32 v9, 0x45800000, v8
	v_cndmask_b32_e64 v126, v8, v9, s[0:1]
	v_pk_mul_f32 v[2:3], v[2:3], v[126:127] op_sel_hi:[1,0]
	v_pk_mul_f32 v[6:7], v[6:7], v[126:127] op_sel_hi:[1,0]
	v_pk_fma_f32 v[8:9], v[38:39], v[2:3], v[40:41]
	v_pk_mul_f32 v[2:3], v[132:133], v[126:127] op_sel_hi:[1,0]
	v_pk_mul_f32 v[4:5], v[4:5], v[126:127] op_sel_hi:[1,0]
	v_pk_fma_f32 v[6:7], v[28:29], v[6:7], v[30:31]
	v_pk_fma_f32 v[2:3], v[46:47], v[2:3], v[48:49]
	v_pk_fma_f32 v[4:5], v[54:55], v[4:5], v[56:57]
	s_mov_b32 s0, 0xffff
	v_cvt_pk_bf16_f32 v126, v6, v7
	v_cvt_pk_bf16_f32 v127, v8, v9
	v_cvt_pk_bf16_f32 v128, v2, v3
	v_cvt_pk_bf16_f32 v129, v4, v5
	v_cmp_lt_i32_e64 s[44:45], s0, v62
	global_store_dwordx4 v[86:87], v[126:129], off offset:1024
	s_and_saveexec_b64 s[0:1], s[44:45]
	s_cbranch_execz .LBB0_423
	v_mov_b32_e32 v109, v1
	v_lshlrev_b64 v[126:127], 11, v[108:109]
	v_lshl_add_u64 v[126:127], v[66:67], 0, v[126:127]
	global_store_dwordx4 v[126:127], v[6:9], off
	global_store_dwordx4 v[126:127], v[2:5], off offset:16
